# loop-edge edit: scalar and address setup hoisted above every attention-loop barrier, back edges rotated with an exit-path barrier copy
# speedup vs baseline: 1.0099x; 1.0088x over previous
; #define LAS __attribute__((address_space(3)))
; #define MFMA32(a, b, c) __builtin_amdgcn_mfma_f32_32x32x16_bf16((a), (b), (c), 0, 0, 0)
; #define AT_ISSUE_V(jn) do { const int jc_ = (jn) < ntm1 ? (jn) : ntm1; const size_t vo_ = (size_t)jc_ * 16384; vs0 = *(const u32x4*)(bV0 + vo_ + voff); vs1 = *(const u32x4*)(bV1 + vo_ + voff); } while (0)
; #define AT_WRITE_K(jn) do { LAS unsigned char* n_ = lds + ((jn) & 1) * AT_KST; *(LAS u32x4*)(n_ + dK1) = ks0; *(LAS u32x4*)(n_ + dK2) = ks1; } while (0)
; __device__ __forceinline__ void at_pv_half(const LAS unsigned char* vp, const bf16x8 (&pf)[4], f32x16 (&O)[4], f32x16& L) {
;     bf16x8 va[8], vb[8];
; #pragma unroll
;     for (int e = 0; e < 2; ++e)
; #pragma unroll
;         for (int ks = 0; ks < 4; ++ks) va[e * 4 + ks] = *(const LAS bf16x8*)(vp + e * 32 * AT_ROWB + 32 * ks);
; #pragma unroll
;     for (int e = 0; e < 2; ++e)
; #pragma unroll
;         for (int ks = 0; ks < 4; ++ks) vb[e * 4 + ks] = *(const LAS bf16x8*)(vp + (2 + e) * 32 * AT_ROWB + 32 * ks);
;     const short one = (short)0x3F80; const bf16x8 ones = {one, one, one, one, one, one, one, one};
;     __builtin_amdgcn_sched_barrier(0);
;     __builtin_amdgcn_s_setprio(1);
; #pragma unroll
;     for (int ks = 0; ks < 4; ++ks) L = MFMA32(ones, pf[ks], L);
;     __builtin_amdgcn_sched_barrier(0);
; #pragma unroll
;     for (int ks = 0; ks < 4; ++ks) { O[0] = MFMA32(va[ks], pf[ks], O[0]); O[1] = MFMA32(va[4 + ks], pf[ks], O[1]); }
; #pragma unroll
;     for (int ks = 0; ks < 4; ++ks) { O[2] = MFMA32(vb[ks], pf[ks], O[2]); O[3] = MFMA32(vb[4 + ks], pf[ks], O[3]); }
;     __builtin_amdgcn_s_setprio(0);
; __device__ __forceinline__ void attn_item(LAS unsigned char* lds, const bf16_t* Q, const bf16_t* Kb, const bf16_t* VT, bf16_t* aout, const float* subg, float lam, float omli, float kbound, int head, int qb) {
;     ...
;         for (int j = 0; j < nt; ++j) {
;             const LAS unsigned char* stg = lds + (j & 1) * AT_KST; const LAS unsigned char* pst = lds + ((j + 1) & 1) * AT_KST; const int kbase = j * 64;
;             AT_ISSUE_V(j + 1);
;             if (j > 0 && kbase - 64 <= qmax) at_pv_half(pst + vfo, pf, O, L);
;             AT_WRITE_K(j + 1);
.LBB0_295:
	s_add_i32 s44, s45, 1
	s_bitcmp1_b32 s44, 0
	s_cselect_b32 s53, 0x4800, 0
	s_min_i32 s58, s44, s41
	s_lshl_b64 s[54:55], s[58:59], 14
	v_lshl_add_u64 v[96:97], v[208:209], 0, s[54:55]
	v_lshl_add_u64 v[98:99], v[210:211], 0, s[54:55]
	global_load_dwordx4 v[146:149], v[96:97], off
	global_load_dwordx4 v[150:153], v[98:99], off
	s_add_i32 s56, s53, 0
	s_cmp_eq_u32 s45, 0
	s_cselect_b64 s[54:55], -1, 0
	s_add_i32 s53, s1, 0xffffff81
	s_cmp_gt_i32 s53, s40
	s_cselect_b64 s[60:61], -1, 0
	s_or_b64 s[54:55], s[54:55], s[60:61]
	s_and_b64 vcc, exec, s[54:55]
	v_add_u32_e32 v184, s56, v228
.Lmy_top1:
	s_cbranch_vccnz .LBB0_297
	ds_read_b128 v[96:99], v184 offset:36864
	ds_read_b128 v[154:157], v184 offset:41472
	ds_read_b128 v[170:173], v184 offset:46080
	ds_read_b128 v[236:239], v184 offset:50688
	ds_read_b128 v[100:103], v184 offset:36896
	ds_read_b128 v[158:161], v184 offset:41504
	ds_read_b128 v[174:177], v184 offset:46112
	ds_read_b128 v[240:243], v184 offset:50720
	ds_read_b128 v[104:107], v184 offset:36928
	ds_read_b128 v[162:165], v184 offset:41536
	ds_read_b128 v[178:181], v184 offset:46144
	ds_read_b128 v[244:247], v184 offset:50752
	ds_read_b128 v[108:111], v184 offset:36960
	ds_read_b128 v[166:169], v184 offset:41568
	ds_read_b128 v[232:235], v184 offset:46176
	ds_read_b128 v[248:251], v184 offset:50784
	s_setprio 1
	v_mfma_f32_16x16x32_bf16 v[64:67], v[76:79], v[80:83], v[64:67]
	v_mfma_f32_16x16x32_bf16 v[64:67], v[76:79], v[88:91], v[64:67]
	v_mfma_f32_16x16x32_bf16 v[64:67], v[76:79], v[84:87], v[64:67]
	v_mfma_f32_16x16x32_bf16 v[64:67], v[76:79], v[92:95], v[64:67]
	v_add_u32_e32 v185, s56, v212
	s_waitcnt vmcnt(3)
	ds_write_b128 v185, v[142:145]
	s_waitcnt vmcnt(2)
	ds_write_b128 v185, v[138:141] offset:9216
	s_waitcnt lgkmcnt(15)
	v_mfma_f32_32x32x16_bf16 v[48:63], v[96:99], v[80:83], v[48:63]
	s_waitcnt lgkmcnt(15)
	v_mfma_f32_32x32x16_bf16 v[32:47], v[154:157], v[80:83], v[32:47]
	s_waitcnt lgkmcnt(15)
	v_mfma_f32_32x32x16_bf16 v[16:31], v[170:173], v[80:83], v[16:31]
	s_waitcnt lgkmcnt(14)
	v_mfma_f32_32x32x16_bf16 v[0:15], v[236:239], v[80:83], v[0:15]
	s_waitcnt lgkmcnt(13)
	v_mfma_f32_32x32x16_bf16 v[48:63], v[100:103], v[88:91], v[48:63]
	s_waitcnt lgkmcnt(12)
	v_mfma_f32_32x32x16_bf16 v[32:47], v[158:161], v[88:91], v[32:47]
	s_waitcnt lgkmcnt(11)
	v_mfma_f32_32x32x16_bf16 v[16:31], v[174:177], v[88:91], v[16:31]
	s_waitcnt lgkmcnt(10)
	v_mfma_f32_32x32x16_bf16 v[0:15], v[240:243], v[88:91], v[0:15]
	s_waitcnt lgkmcnt(9)
	v_mfma_f32_32x32x16_bf16 v[48:63], v[104:107], v[84:87], v[48:63]
	s_waitcnt lgkmcnt(8)
	v_mfma_f32_32x32x16_bf16 v[32:47], v[162:165], v[84:87], v[32:47]
	s_waitcnt lgkmcnt(7)
	v_mfma_f32_32x32x16_bf16 v[16:31], v[178:181], v[84:87], v[16:31]
	s_waitcnt lgkmcnt(6)
	v_mfma_f32_32x32x16_bf16 v[0:15], v[244:247], v[84:87], v[0:15]
	s_waitcnt lgkmcnt(5)
	v_mfma_f32_32x32x16_bf16 v[48:63], v[108:111], v[92:95], v[48:63]
	s_waitcnt lgkmcnt(4)
	v_mfma_f32_32x32x16_bf16 v[32:47], v[166:169], v[92:95], v[32:47]
	s_waitcnt lgkmcnt(3)
	v_mfma_f32_32x32x16_bf16 v[16:31], v[232:235], v[92:95], v[16:31]
	s_waitcnt lgkmcnt(2)
	v_mfma_f32_32x32x16_bf16 v[0:15], v[248:251], v[92:95], v[0:15]
	s_setprio 0
	s_branch .Lmy_wj1

; __device__ __forceinline__ void at_qk_half(const bool ONLINE, const bool act, const LAS unsigned char* kp, u32x4& pfa, u32x4& pfb, const char* pga, const char* pgb, const bf16x8 (&qf)[4], int q, int q0, int kbase, int hh, float& mrun, f32x16 (&O)[4], f32x16& L, bf16x8 (&pf)[4]) {
;     __builtin_amdgcn_s_setprio(3);
;     bf16x8 kf[8];
; #pragma unroll
;     for (int s = 0; s < 4; ++s) { kf[2 * s] = *(const LAS bf16x8*)(kp + 32 * s); kf[2 * s + 1] = *(const LAS bf16x8*)(kp + 32 * AT_ROWB + 32 * s); }
;     __builtin_amdgcn_sched_barrier(0);
;     pfa = *(const u32x4*)pga; pfb = *(const u32x4*)pgb;
;     __builtin_amdgcn_sched_barrier(0);
;     if (!act) { __builtin_amdgcn_s_setprio(0); return; }
;     f32x16 s0, s1;
; #pragma unroll
;     for (int i = 0; i < 16; ++i) { s0[i] = 0.f; s1[i] = 0.f; }
; #pragma unroll
;     for (int s = 0; s < 4; ++s) { s0 = MFMA32(kf[2 * s], qf[s], s0); s1 = MFMA32(kf[2 * s + 1], qf[s], s1); }
;     __builtin_amdgcn_s_setprio(0);
;     if (kbase + 63 > q0) {
;         const int kb = kbase + 4 * hh;
; #pragma unroll
;         for (int i = 0; i < 16; ++i) { const int kv = kb + (i & 3) + 8 * (i >> 2); if (kv > q) s0[i] = -INFINITY; if (kv + 32 > q) s1[i] = -INFINITY; }
;     }
;     if (ONLINE) {
; #pragma unroll
;         for (int i = 0; i < 16; ++i) { s0[i] -= mrun; s1[i] -= mrun; }
;         float mx = fmaxf(s0[0], s1[0]);
; #pragma unroll
;         for (int i = 1; i < 16; ++i) mx = at_max3(mx, s0[i], s1[i]);
;         mx = half_swap_max(mx);
;         if (__builtin_amdgcn_ballot_w64(mx > 8.f) != 0ull) {
;             const float d = fmaxf(mx, 0.f); const float alpha = __builtin_amdgcn_exp2f(-d); mrun += d;
; #pragma unroll
;             for (int e = 0; e < 4; ++e)
; #pragma unroll
;                 for (int i = 0; i < 16; ++i) O[e][i] *= alpha;
; __device__ __forceinline__ void attn_item(LAS unsigned char* lds, const bf16_t* Q, const bf16_t* Kb, const bf16_t* VT, bf16_t* aout, const float* subg, float lam, float omli, float kbound, int head, int qb) {
;     ...
;             __syncthreads();
;             __builtin_amdgcn_s_setprio(3);
;             { const int jc_ = (j + 2) < ntm1 ? (j + 2) : ntm1; const size_t ko_ = (size_t)jc_ * 8192; const char* pga = bK1 + ko_ + koff; const char* pgb = bK2 + ko_ + koff;
;               at_qk_half(online, kbase <= qmax, stg + kfo, ks0, ks1, pga, pgb, qf, q, q0, kbase, hh, mrun, O, L, pf); }
.Lmy_wj1:
	v_add_u32_e32 v232, s56, v212
	s_bitcmp1_b32 s45, 0
	s_cselect_b32 s53, 0x4800, 0
	s_sub_i32 s57, s1, 63
	s_add_i32 s45, s45, 2
	s_min_i32 s58, s45, s41
	s_lshl_b64 s[54:55], s[58:59], 13
	v_lshl_add_u64 v[100:101], v[204:205], 0, s[54:55]
	v_lshl_add_u64 v[102:103], v[206:207], 0, s[54:55]
	v_add_u32_e32 v104, s53, v230
	s_cmp_gt_i32 s57, s40
	s_waitcnt lgkmcnt(0)
	s_barrier
	s_setprio 3
	ds_read_b128 v[96:99], v104
	ds_read_b128 v[166:169], v104 offset:32
	ds_read_b128 v[162:165], v104 offset:64
	ds_read_b128 v[154:157], v104 offset:96
	ds_read_b128 v[178:181], v104 offset:4608
	ds_read_b128 v[170:173], v104 offset:4640
	ds_read_b128 v[174:177], v104 offset:4672
	ds_read_b128 v[158:161], v104 offset:4704
	global_load_dwordx4 v[142:145], v[100:101], off
	global_load_dwordx4 v[138:141], v[102:103], off
	s_cbranch_scc1 .LBB0_304
	s_cmp_le_i32 s1, s33
	s_cbranch_scc0 .Lmy_slow1
	s_andn2_b64 vcc, exec, s[64:65]
	s_cbranch_vccz .Lmy_slow1
	s_waitcnt lgkmcnt(7)
	v_mfma_f32_32x32x16_bf16 v[96:111], v[96:99], v[126:129], 0
	s_waitcnt lgkmcnt(6)
	v_mfma_f32_32x32x16_bf16 v[96:111], v[166:169], v[122:125], v[96:111]
	s_waitcnt lgkmcnt(5)
	v_mfma_f32_32x32x16_bf16 v[96:111], v[162:165], v[118:121], v[96:111]
	s_waitcnt lgkmcnt(4)
	v_mfma_f32_32x32x16_bf16 v[96:111], v[154:157], v[114:117], v[96:111]
	s_waitcnt lgkmcnt(3)
	v_mfma_f32_32x32x16_bf16 v[80:95], v[178:181], v[126:129], 0
	s_waitcnt lgkmcnt(2)
	v_mfma_f32_32x32x16_bf16 v[80:95], v[170:173], v[122:125], v[80:95]
	s_nop 8
	v_exp_f32_e32 v96, v96
	v_exp_f32_e32 v97, v97
	v_exp_f32_e32 v98, v98
	v_exp_f32_e32 v99, v99
	s_waitcnt lgkmcnt(1)
	v_mfma_f32_32x32x16_bf16 v[80:95], v[174:177], v[118:121], v[80:95]
	v_exp_f32_e32 v100, v100
	v_exp_f32_e32 v101, v101
	v_exp_f32_e32 v102, v102
	v_exp_f32_e32 v103, v103
	s_waitcnt lgkmcnt(0)
	v_mfma_f32_32x32x16_bf16 v[80:95], v[158:161], v[114:117], v[80:95]
	s_setprio 0
	v_exp_f32_e32 v104, v104
	v_exp_f32_e32 v105, v105
	v_exp_f32_e32 v106, v106
	v_exp_f32_e32 v107, v107
	v_exp_f32_e32 v108, v108
	v_exp_f32_e32 v109, v109
	v_exp_f32_e32 v110, v110
	v_exp_f32_e32 v111, v111
	s_nop 3
	v_exp_f32_e32 v154, v80
	v_exp_f32_e32 v155, v81
	v_exp_f32_e32 v156, v82
	v_exp_f32_e32 v157, v83
	v_exp_f32_e32 v158, v84
	v_exp_f32_e32 v159, v85
	v_exp_f32_e32 v160, v86
	v_exp_f32_e32 v161, v87
	v_exp_f32_e32 v162, v88
	v_exp_f32_e32 v163, v89
	v_exp_f32_e32 v164, v90
	v_exp_f32_e32 v165, v91
	v_exp_f32_e32 v166, v92
	v_exp_f32_e32 v167, v93
	v_exp_f32_e32 v168, v94
	v_exp_f32_e32 v169, v95
	v_cvt_pk_bf16_f32 v80, v96, v97
	v_cvt_pk_bf16_f32 v81, v98, v99
	v_cvt_pk_bf16_f32 v82, v100, v101
	v_cvt_pk_bf16_f32 v83, v102, v103
	v_cvt_pk_bf16_f32 v84, v154, v155
	v_cvt_pk_bf16_f32 v85, v156, v157
	v_cvt_pk_bf16_f32 v86, v158, v159
	v_cvt_pk_bf16_f32 v87, v160, v161
	v_cvt_pk_bf16_f32 v88, v104, v105
	v_cvt_pk_bf16_f32 v89, v106, v107
	v_cvt_pk_bf16_f32 v90, v108, v109
	v_cvt_pk_bf16_f32 v91, v110, v111
	v_cvt_pk_bf16_f32 v92, v162, v163
	v_cvt_pk_bf16_f32 v93, v164, v165
	v_cvt_pk_bf16_f32 v94, v166, v167
	v_cvt_pk_bf16_f32 v95, v168, v169
	s_branch .LBB0_304

; #define LAS __attribute__((address_space(3)))
; #define AT_ISSUE_V(jn) do { const int jc_ = (jn) < ntm1 ? (jn) : ntm1; const size_t vo_ = (size_t)jc_ * 16384; vs0 = *(const u32x4*)(bV0 + vo_ + voff); vs1 = *(const u32x4*)(bV1 + vo_ + voff); } while (0)
; #define AT_WRITE_K(jn) do { LAS unsigned char* n_ = lds + ((jn) & 1) * AT_KST; *(LAS u32x4*)(n_ + dK1) = ks0; *(LAS u32x4*)(n_ + dK2) = ks1; } while (0)
; #define AT_WRITE_V(jn) do { LAS unsigned char* n_ = lds + ((jn) & 1) * AT_KST; *(LAS u32x4*)(n_ + dV0) = vs0; *(LAS u32x4*)(n_ + dV1) = vs1; } while (0)
; __device__ __forceinline__ void attn_item(LAS unsigned char* lds, const bf16_t* Q, const bf16_t* Kb, const bf16_t* VT, bf16_t* aout, const float* subg, float lam, float omli, float kbound, int head, int qb) {
;     ...
;         for (int j = 0; j < nt; ++j) {
;             const LAS unsigned char* stg = lds + (j & 1) * AT_KST; const LAS unsigned char* pst = lds + ((j + 1) & 1) * AT_KST; const int kbase = j * 64;
;             AT_ISSUE_V(j + 1);
;             if (j > 0 && kbase - 64 <= qmax) at_pv_half(pst + vfo, pf, O, L);
;             AT_WRITE_K(j + 1);
;             __syncthreads();
;             __builtin_amdgcn_s_setprio(3);
;             { const int jc_ = (j + 2) < ntm1 ? (j + 2) : ntm1; const size_t ko_ = (size_t)jc_ * 8192; const char* pga = bK1 + ko_ + koff; const char* pgb = bK2 + ko_ + koff;
;               at_qk_half(online, kbase <= qmax, stg + kfo, ks0, ks1, pga, pgb, qf, q, q0, kbase, hh, mrun, O, L, pf); }
;             __builtin_amdgcn_s_setprio(3);
;             AT_WRITE_V(j + 1);
;             __syncthreads();
;             __builtin_amdgcn_s_setprio(0);
;         }
.LBB0_304:
	s_setprio 3
	s_waitcnt vmcnt(3)
	ds_write_b128 v232, v[146:149] offset:36864
	s_waitcnt vmcnt(2)
	ds_write_b128 v232, v[150:153] offset:46080
	s_waitcnt lgkmcnt(0)
	s_add_i32 s1, s1, 64
	s_cmp_eq_u32 s0, s44
	s_cbranch_scc1 .Lmy_exit1
	s_mov_b32 s45, s44
	s_add_i32 s44, s45, 1
	s_bitcmp1_b32 s44, 0
	s_cselect_b32 s53, 0x4800, 0
	s_min_i32 s58, s44, s41
	s_lshl_b64 s[54:55], s[58:59], 14
	v_lshl_add_u64 v[96:97], v[208:209], 0, s[54:55]
	v_lshl_add_u64 v[98:99], v[210:211], 0, s[54:55]
	global_load_dwordx4 v[146:149], v[96:97], off
	global_load_dwordx4 v[150:153], v[98:99], off
	s_add_i32 s56, s53, 0
	s_cmp_eq_u32 s45, 0
	s_cselect_b64 s[54:55], -1, 0
	s_add_i32 s53, s1, 0xffffff81
	s_cmp_gt_i32 s53, s40
	s_cselect_b64 s[60:61], -1, 0
	s_or_b64 s[54:55], s[54:55], s[60:61]
	s_and_b64 vcc, exec, s[54:55]
	v_add_u32_e32 v184, s56, v228
	s_barrier
	s_setprio 0
	s_branch .Lmy_top1
.Lmy_exit1:
	s_barrier
	s_setprio 0
	s_branch .LBB0_307

; __device__ __forceinline__ void at_qk_half(const bool ONLINE, const bool act, const LAS unsigned char* kp, u32x4& pfa, u32x4& pfb, const char* pga, const char* pgb, const bf16x8 (&qf)[4], int q, int q0, int kbase, int hh, float& mrun, f32x16 (&O)[4], f32x16& L, bf16x8 (&pf)[4]) {
;     __builtin_amdgcn_s_setprio(3);
;     bf16x8 kf[8];
; #pragma unroll
;     for (int s = 0; s < 4; ++s) { kf[2 * s] = *(const LAS bf16x8*)(kp + 32 * s); kf[2 * s + 1] = *(const LAS bf16x8*)(kp + 32 * AT_ROWB + 32 * s); }
;     __builtin_amdgcn_sched_barrier(0);
;     pfa = *(const u32x4*)pga; pfb = *(const u32x4*)pgb;
;     __builtin_amdgcn_sched_barrier(0);
;     if (!act) { __builtin_amdgcn_s_setprio(0); return; }
;     f32x16 s0, s1;
; #pragma unroll
;     for (int i = 0; i < 16; ++i) { s0[i] = 0.f; s1[i] = 0.f; }
; #pragma unroll
;     for (int s = 0; s < 4; ++s) { s0 = MFMA32(kf[2 * s], qf[s], s0); s1 = MFMA32(kf[2 * s + 1], qf[s], s1); }
;     __builtin_amdgcn_s_setprio(0);
;     if (kbase + 63 > q0) {
;         const int kb = kbase + 4 * hh;
; #pragma unroll
;         for (int i = 0; i < 16; ++i) { const int kv = kb + (i & 3) + 8 * (i >> 2); if (kv > q) s0[i] = -INFINITY; if (kv + 32 > q) s1[i] = -INFINITY; }
;     }
;     if (ONLINE) {
; #pragma unroll
;         for (int i = 0; i < 16; ++i) { s0[i] -= mrun; s1[i] -= mrun; }
;         float mx = fmaxf(s0[0], s1[0]);
; #pragma unroll
;         for (int i = 1; i < 16; ++i) mx = at_max3(mx, s0[i], s1[i]);
;         mx = half_swap_max(mx);
;         if (__builtin_amdgcn_ballot_w64(mx > 8.f) != 0ull) {
;             const float d = fmaxf(mx, 0.f); const float alpha = __builtin_amdgcn_exp2f(-d); mrun += d;
; #pragma unroll
;             for (int e = 0; e < 4; ++e)
; __device__ __forceinline__ void attn_item(LAS unsigned char* lds, const bf16_t* Q, const bf16_t* Kb, const bf16_t* VT, bf16_t* aout, const float* subg, float lam, float omli, float kbound, int head, int qb) {
;     ...
;             const LAS unsigned char* stg = lds + (j & 1) * AT_KST; const int kbase = j * 64; const bool act = kbase <= qmax;
;             __builtin_amdgcn_s_setprio(3);
;             { const int jc_ = (j + 1) < ntm1 ? (j + 1) : ntm1; const size_t vo_ = (size_t)jc_ * 16384; const char* pga = bV0 + vo_ + voff; const char* pgb = bV1 + vo_ + voff;
;               at_qk_half(online, act, stg + kfo, vs0, vs1, pga, pgb, qf, q, q0, kbase, hh, mrun, O, L, pf); }
.Lmy_top3:
	ds_read_b128 v[96:99], v104
	ds_read_b128 v[158:161], v104 offset:32
	ds_read_b128 v[154:157], v104 offset:64
	ds_read_b128 v[146:149], v104 offset:96
	ds_read_b128 v[170:173], v104 offset:4608
	ds_read_b128 v[162:165], v104 offset:4640
	ds_read_b128 v[166:169], v104 offset:4672
	ds_read_b128 v[150:153], v104 offset:4704
	global_load_dwordx4 v[138:141], v[100:101], off
	global_load_dwordx4 v[142:145], v[102:103], off
	s_cbranch_scc1 .LBB0_320
	s_cmp_le_i32 s45, s33
	s_cbranch_scc0 .Lmy_slow2
	s_andn2_b64 vcc, exec, s[64:65]
	s_cbranch_vccz .Lmy_slow2
	s_waitcnt lgkmcnt(7)
	v_mfma_f32_32x32x16_bf16 v[96:111], v[96:99], v[126:129], 0
	s_waitcnt lgkmcnt(6)
	v_mfma_f32_32x32x16_bf16 v[96:111], v[158:161], v[122:125], v[96:111]
	s_waitcnt lgkmcnt(5)
	v_mfma_f32_32x32x16_bf16 v[96:111], v[154:157], v[118:121], v[96:111]
	s_waitcnt lgkmcnt(4)
	v_mfma_f32_32x32x16_bf16 v[96:111], v[146:149], v[114:117], v[96:111]
	s_waitcnt lgkmcnt(3)
	v_mfma_f32_32x32x16_bf16 v[80:95], v[170:173], v[126:129], 0
	s_waitcnt lgkmcnt(2)
	v_mfma_f32_32x32x16_bf16 v[80:95], v[162:165], v[122:125], v[80:95]
	s_nop 8
	v_exp_f32_e32 v96, v96
	v_exp_f32_e32 v97, v97
	v_exp_f32_e32 v98, v98
	v_exp_f32_e32 v99, v99
	s_waitcnt lgkmcnt(1)
	v_mfma_f32_32x32x16_bf16 v[80:95], v[166:169], v[118:121], v[80:95]
	v_exp_f32_e32 v100, v100
	v_exp_f32_e32 v101, v101
	v_exp_f32_e32 v102, v102
	v_exp_f32_e32 v103, v103
	s_waitcnt lgkmcnt(0)
	v_mfma_f32_32x32x16_bf16 v[80:95], v[150:153], v[114:117], v[80:95]
	s_setprio 0
	v_exp_f32_e32 v104, v104
	v_exp_f32_e32 v105, v105
	v_exp_f32_e32 v106, v106
	v_exp_f32_e32 v107, v107
	v_exp_f32_e32 v108, v108
	v_exp_f32_e32 v109, v109
	v_exp_f32_e32 v110, v110
	v_exp_f32_e32 v111, v111
	s_nop 3
	v_exp_f32_e32 v146, v80
	v_exp_f32_e32 v147, v81
	v_exp_f32_e32 v148, v82
	v_exp_f32_e32 v149, v83
	v_exp_f32_e32 v150, v84
	v_exp_f32_e32 v151, v85
	v_exp_f32_e32 v152, v86
	v_exp_f32_e32 v153, v87
	v_exp_f32_e32 v154, v88
	v_exp_f32_e32 v155, v89
	v_exp_f32_e32 v156, v90
	v_exp_f32_e32 v157, v91
	v_exp_f32_e32 v158, v92
	v_exp_f32_e32 v159, v93
	v_exp_f32_e32 v160, v94
	v_exp_f32_e32 v161, v95
	v_cvt_pk_bf16_f32 v80, v96, v97
	v_cvt_pk_bf16_f32 v81, v98, v99
	v_cvt_pk_bf16_f32 v82, v100, v101
	v_cvt_pk_bf16_f32 v83, v102, v103
	v_cvt_pk_bf16_f32 v84, v146, v147
	v_cvt_pk_bf16_f32 v85, v148, v149
	v_cvt_pk_bf16_f32 v86, v150, v151
	v_cvt_pk_bf16_f32 v87, v152, v153
	v_cvt_pk_bf16_f32 v88, v104, v105
	v_cvt_pk_bf16_f32 v89, v106, v107
	v_cvt_pk_bf16_f32 v90, v108, v109
	v_cvt_pk_bf16_f32 v91, v110, v111
	v_cvt_pk_bf16_f32 v92, v154, v155
	v_cvt_pk_bf16_f32 v93, v156, v157
	v_cvt_pk_bf16_f32 v94, v158, v159
	v_cvt_pk_bf16_f32 v95, v160, v161
	s_branch .LBB0_320

; #define LAS __attribute__((address_space(3)))
; #define MFMA32(a, b, c) __builtin_amdgcn_mfma_f32_32x32x16_bf16((a), (b), (c), 0, 0, 0)
; #define AT_ISSUE_K(jn) do { const int jc_ = (jn) < ntm1 ? (jn) : ntm1; const size_t ko_ = (size_t)jc_ * 8192; ks0 = *(const u32x4*)(bK1 + ko_ + koff); ks1 = *(const u32x4*)(bK2 + ko_ + koff); } while (0)
; #define AT_WRITE_K(jn) do { LAS unsigned char* n_ = lds + ((jn) & 1) * AT_KST; *(LAS u32x4*)(n_ + dK1) = ks0; *(LAS u32x4*)(n_ + dK2) = ks1; } while (0)
; #define AT_WRITE_V(jn) do { LAS unsigned char* n_ = lds + ((jn) & 1) * AT_KST; *(LAS u32x4*)(n_ + dV0) = vs0; *(LAS u32x4*)(n_ + dV1) = vs1; } while (0)
; __device__ __forceinline__ void at_pv_half(const LAS unsigned char* vp, const bf16x8 (&pf)[4], f32x16 (&O)[4], f32x16& L) {
;     bf16x8 va[8], vb[8];
; #pragma unroll
;     for (int e = 0; e < 2; ++e)
; #pragma unroll
;         for (int ks = 0; ks < 4; ++ks) va[e * 4 + ks] = *(const LAS bf16x8*)(vp + e * 32 * AT_ROWB + 32 * ks);
; #pragma unroll
;     for (int e = 0; e < 2; ++e)
; #pragma unroll
;         for (int ks = 0; ks < 4; ++ks) vb[e * 4 + ks] = *(const LAS bf16x8*)(vp + (2 + e) * 32 * AT_ROWB + 32 * ks);
;     const short one = (short)0x3F80; const bf16x8 ones = {one, one, one, one, one, one, one, one};
;     __builtin_amdgcn_sched_barrier(0);
;     __builtin_amdgcn_s_setprio(1);
; #pragma unroll
;     for (int ks = 0; ks < 4; ++ks) L = MFMA32(ones, pf[ks], L);
;     __builtin_amdgcn_sched_barrier(0);
; #pragma unroll
;     for (int ks = 0; ks < 4; ++ks) { O[0] = MFMA32(va[ks], pf[ks], O[0]); O[1] = MFMA32(va[4 + ks], pf[ks], O[1]); }
; #pragma unroll
;     for (int ks = 0; ks < 4; ++ks) { O[2] = MFMA32(vb[ks], pf[ks], O[2]); O[3] = MFMA32(vb[4 + ks], pf[ks], O[3]); }
;     __builtin_amdgcn_s_setprio(0);
; __device__ __forceinline__ void attn_item(LAS unsigned char* lds, const bf16_t* Q, const bf16_t* Kb, const bf16_t* VT, bf16_t* aout, const float* subg, float lam, float omli, float kbound, int head, int qb) {
;     ...
;             __builtin_amdgcn_s_setprio(3);
;             AT_WRITE_K(j + 1);
;             __syncthreads();
;             __builtin_amdgcn_s_setprio(0);
;             AT_ISSUE_K(j + 2);
;             if (act) at_pv_half(stg + vfo, pf, O, L);
;             AT_WRITE_V(j + 1);
;             __syncthreads();
.LBB0_320:
	s_setprio 3
	s_bitcmp1_b32 s56, 0
	s_cselect_b32 s55, 0x4800, 0
	s_waitcnt lgkmcnt(7)
	v_add_u32_e32 v96, s55, v213
	s_waitcnt vmcnt(3)
	ds_write_b128 v96, v[130:133]
	s_waitcnt vmcnt(2)
	ds_write_b128 v96, v[134:137] offset:9216
	s_waitcnt lgkmcnt(0)
	s_add_i32 s53, s53, 2
	s_min_i32 s58, s53, s41
	s_lshl_b64 s[60:61], s[58:59], 13
	v_lshl_add_u64 v[98:99], v[204:205], 0, s[60:61]
	v_lshl_add_u64 v[100:101], v[206:207], 0, s[60:61]
	global_load_dwordx4 v[130:133], v[98:99], off
	global_load_dwordx4 v[134:137], v[100:101], off
	s_andn2_b64 vcc, exec, s[0:1]
	v_add_u32_e32 v97, s54, v228
	s_barrier
	s_setprio 0
	s_cbranch_vccnz .LBB0_322
	ds_read_b128 v[98:101], v97 offset:36864
	ds_read_b128 v[150:153], v97 offset:41472
	ds_read_b128 v[166:169], v97 offset:46080
	ds_read_b128 v[234:237], v97 offset:50688
	ds_read_b128 v[102:105], v97 offset:36896
	ds_read_b128 v[154:157], v97 offset:41504
	ds_read_b128 v[170:173], v97 offset:46112
	ds_read_b128 v[238:241], v97 offset:50720
	ds_read_b128 v[106:109], v97 offset:36928
	ds_read_b128 v[158:161], v97 offset:41536
	ds_read_b128 v[176:179], v97 offset:46144
	ds_read_b128 v[242:245], v97 offset:50752
	ds_read_b128 v[146:149], v97 offset:36960
	ds_read_b128 v[162:165], v97 offset:41568
	ds_read_b128 v[230:233], v97 offset:46176
	ds_read_b128 v[246:249], v97 offset:50784
	s_setprio 1
	v_mfma_f32_16x16x32_bf16 v[64:67], v[76:79], v[80:83], v[64:67]
	v_mfma_f32_16x16x32_bf16 v[64:67], v[76:79], v[88:91], v[64:67]
	v_mfma_f32_16x16x32_bf16 v[64:67], v[76:79], v[84:87], v[64:67]
	v_mfma_f32_16x16x32_bf16 v[64:67], v[76:79], v[92:95], v[64:67]
	s_waitcnt vmcnt(3)
	ds_write_b128 v96, v[138:141] offset:36864
	s_waitcnt vmcnt(2)
	ds_write_b128 v96, v[142:145] offset:46080
	s_waitcnt lgkmcnt(15)
	v_mfma_f32_32x32x16_bf16 v[48:63], v[98:101], v[80:83], v[48:63]
	s_waitcnt lgkmcnt(15)
	v_mfma_f32_32x32x16_bf16 v[32:47], v[150:153], v[80:83], v[32:47]
	s_waitcnt lgkmcnt(15)
	v_mfma_f32_32x32x16_bf16 v[16:31], v[166:169], v[80:83], v[16:31]
	s_waitcnt lgkmcnt(14)
	v_mfma_f32_32x32x16_bf16 v[0:15], v[234:237], v[80:83], v[0:15]
	s_waitcnt lgkmcnt(13)
	v_mfma_f32_32x32x16_bf16 v[48:63], v[102:105], v[88:91], v[48:63]
	s_waitcnt lgkmcnt(12)
	v_mfma_f32_32x32x16_bf16 v[32:47], v[154:157], v[88:91], v[32:47]
	s_waitcnt lgkmcnt(11)
	v_mfma_f32_32x32x16_bf16 v[16:31], v[170:173], v[88:91], v[16:31]
	s_waitcnt lgkmcnt(10)
	v_mfma_f32_32x32x16_bf16 v[0:15], v[238:241], v[88:91], v[0:15]
	s_waitcnt lgkmcnt(9)
	v_mfma_f32_32x32x16_bf16 v[48:63], v[106:109], v[84:87], v[48:63]
	s_waitcnt lgkmcnt(8)
	v_mfma_f32_32x32x16_bf16 v[32:47], v[158:161], v[84:87], v[32:47]
	s_waitcnt lgkmcnt(7)
	v_mfma_f32_32x32x16_bf16 v[16:31], v[176:179], v[84:87], v[16:31]
	s_waitcnt lgkmcnt(6)
	v_mfma_f32_32x32x16_bf16 v[0:15], v[242:245], v[84:87], v[0:15]
	s_waitcnt lgkmcnt(5)
	v_mfma_f32_32x32x16_bf16 v[48:63], v[146:149], v[92:95], v[48:63]
	s_waitcnt lgkmcnt(4)
	v_mfma_f32_32x32x16_bf16 v[32:47], v[162:165], v[92:95], v[32:47]
	s_waitcnt lgkmcnt(3)
	v_mfma_f32_32x32x16_bf16 v[16:31], v[230:233], v[92:95], v[16:31]
	s_waitcnt lgkmcnt(2)
	v_mfma_f32_32x32x16_bf16 v[0:15], v[246:249], v[92:95], v[0:15]
	s_setprio 0
	s_branch .Lmy_wj3

; #define LAS __attribute__((address_space(3)))
; #define AT_ISSUE_K(jn) do { const int jc_ = (jn) < ntm1 ? (jn) : ntm1; const size_t ko_ = (size_t)jc_ * 8192; ks0 = *(const u32x4*)(bK1 + ko_ + koff); ks1 = *(const u32x4*)(bK2 + ko_ + koff); } while (0)
; #define AT_WRITE_K(jn) do { LAS unsigned char* n_ = lds + ((jn) & 1) * AT_KST; *(LAS u32x4*)(n_ + dK1) = ks0; *(LAS u32x4*)(n_ + dK2) = ks1; } while (0)
; #define AT_WRITE_V(jn) do { LAS unsigned char* n_ = lds + ((jn) & 1) * AT_KST; *(LAS u32x4*)(n_ + dV0) = vs0; *(LAS u32x4*)(n_ + dV1) = vs1; } while (0)
; __device__ __forceinline__ void attn_item(LAS unsigned char* lds, const bf16_t* Q, const bf16_t* Kb, const bf16_t* VT, bf16_t* aout, const float* subg, float lam, float omli, float kbound, int head, int qb) {
;     ...
;         for (int j = 0; j < nt; ++j) {
;             const LAS unsigned char* stg = lds + (j & 1) * AT_KST; const int kbase = j * 64; const bool act = kbase <= qmax;
;             __builtin_amdgcn_s_setprio(3);
;             { const int jc_ = (j + 1) < ntm1 ? (j + 1) : ntm1; const size_t vo_ = (size_t)jc_ * 16384; const char* pga = bV0 + vo_ + voff; const char* pgb = bV1 + vo_ + voff;
;               at_qk_half(online, act, stg + kfo, vs0, vs1, pga, pgb, qf, q, q0, kbase, hh, mrun, O, L, pf); }
;             __builtin_amdgcn_s_setprio(3);
;             AT_WRITE_K(j + 1);
;             __syncthreads();
;             __builtin_amdgcn_s_setprio(0);
;             AT_ISSUE_K(j + 2);
;             if (act) at_pv_half(stg + vfo, pf, O, L);
;             AT_WRITE_V(j + 1);
;             __syncthreads();
;         }
.Lmy_wj3:
	s_add_i32 s45, s45, 64
	s_cmp_eq_u32 s44, s56
	s_cbranch_scc1 .Lmy_exit3
	s_mov_b32 s53, s56
	s_bitcmp1_b32 s53, 0
	s_cselect_b32 s0, 0x4800, 0
	s_add_i32 s54, s0, 0
	s_sub_i32 s55, s45, 63
	s_cmp_le_i32 s55, s40
	s_cselect_b64 s[0:1], -1, 0
	s_add_i32 s56, s53, 1
	s_min_i32 s58, s56, s41
	s_lshl_b64 s[60:61], s[58:59], 14
	s_cmp_gt_i32 s55, s40
	v_lshl_add_u64 v[100:101], v[208:209], 0, s[60:61]
	v_lshl_add_u64 v[102:103], v[210:211], 0, s[60:61]
	v_add_u32_e32 v104, s54, v229
	s_waitcnt lgkmcnt(0)
	s_barrier
	s_setprio 3
	s_branch .Lmy_top3
.Lmy_exit3:
	s_waitcnt lgkmcnt(0)
	s_barrier
	s_branch .LBB0_325

; #define LAS __attribute__((address_space(3)))
; #define MFMA32(a, b, c) __builtin_amdgcn_mfma_f32_32x32x16_bf16((a), (b), (c), 0, 0, 0)
; #define AT_ISSUE_V(jn) do { const int jc_ = (jn) < ntm1 ? (jn) : ntm1; const size_t vo_ = (size_t)jc_ * 16384; vs0 = *(const u32x4*)(bV0 + vo_ + voff); vs1 = *(const u32x4*)(bV1 + vo_ + voff); } while (0)
; #define AT_WRITE_K(jn) do { LAS unsigned char* n_ = lds + ((jn) & 1) * AT_KST; *(LAS u32x4*)(n_ + dK1) = ks0; *(LAS u32x4*)(n_ + dK2) = ks1; } while (0)
; __device__ __forceinline__ void at_pv_half(const LAS unsigned char* vp, const bf16x8 (&pf)[4], f32x16 (&O)[4], f32x16& L) {
;     bf16x8 va[8], vb[8];
; #pragma unroll
;     for (int e = 0; e < 2; ++e)
; #pragma unroll
;         for (int ks = 0; ks < 4; ++ks) va[e * 4 + ks] = *(const LAS bf16x8*)(vp + e * 32 * AT_ROWB + 32 * ks);
; #pragma unroll
;     for (int e = 0; e < 2; ++e)
; #pragma unroll
;         for (int ks = 0; ks < 4; ++ks) vb[e * 4 + ks] = *(const LAS bf16x8*)(vp + (2 + e) * 32 * AT_ROWB + 32 * ks);
;     const short one = (short)0x3F80; const bf16x8 ones = {one, one, one, one, one, one, one, one};
;     __builtin_amdgcn_sched_barrier(0);
;     __builtin_amdgcn_s_setprio(1);
; #pragma unroll
;     for (int ks = 0; ks < 4; ++ks) L = MFMA32(ones, pf[ks], L);
;     __builtin_amdgcn_sched_barrier(0);
; #pragma unroll
;     for (int ks = 0; ks < 4; ++ks) { O[0] = MFMA32(va[ks], pf[ks], O[0]); O[1] = MFMA32(va[4 + ks], pf[ks], O[1]); }
; #pragma unroll
;     for (int ks = 0; ks < 4; ++ks) { O[2] = MFMA32(vb[ks], pf[ks], O[2]); O[3] = MFMA32(vb[4 + ks], pf[ks], O[3]); }
;     __builtin_amdgcn_s_setprio(0);
; __device__ __forceinline__ void attn_item(LAS unsigned char* lds, const bf16_t* Q, const bf16_t* Kb, const bf16_t* VT, bf16_t* aout, const float* subg, float lam, float omli, float kbound, int head, int qb) {
;     ...
;         for (int j = 0; j < nt; ++j) {
;             const LAS unsigned char* stg = lds + (j & 1) * AT_KST; const LAS unsigned char* pst = lds + ((j + 1) & 1) * AT_KST; const int kbase = j * 64;
;             AT_ISSUE_V(j + 1);
;             if (j > 0 && kbase - 64 <= qmax) at_pv_half(pst + vfo, pf, O, L);
;             AT_WRITE_K(j + 1);
.LBB0_333:
	s_add_i32 s38, s39, 1
	s_bitcmp1_b32 s38, 0
	s_cselect_b32 s42, 0x4800, 0
	s_min_i32 s58, s38, s22
	s_lshl_b64 s[40:41], s[58:59], 14
	v_lshl_add_u64 v[96:97], v[208:209], 0, s[40:41]
	v_lshl_add_u64 v[98:99], v[210:211], 0, s[40:41]
	global_load_dwordx4 v[146:149], v[96:97], off
	global_load_dwordx4 v[150:153], v[98:99], off
	s_add_i32 s40, s42, 0
	s_cmp_eq_u32 s39, 0
	s_cselect_b64 s[42:43], -1, 0
	s_add_i32 s41, s1, 0xffffff81
	s_cmp_gt_i32 s41, s21
	s_cselect_b64 s[44:45], -1, 0
	s_or_b64 s[42:43], s[42:43], s[44:45]
	s_and_b64 vcc, exec, s[42:43]
	v_add_u32_e32 v244, s40, v228
.Lmy_top4:
	s_cbranch_vccnz .LBB0_335
	ds_read_b128 v[96:99], v244 offset:36864
	ds_read_b128 v[154:157], v244 offset:41472
	ds_read_b128 v[170:173], v244 offset:46080
	ds_read_b128 v[232:235], v244 offset:50688
	ds_read_b128 v[100:103], v244 offset:36896
	ds_read_b128 v[158:161], v244 offset:41504
	ds_read_b128 v[174:177], v244 offset:46112
	ds_read_b128 v[236:239], v244 offset:50720
	ds_read_b128 v[104:107], v244 offset:36928
	ds_read_b128 v[162:165], v244 offset:41536
	ds_read_b128 v[178:181], v244 offset:46144
	ds_read_b128 v[240:243], v244 offset:50752
	ds_read_b128 v[108:111], v244 offset:36960
	ds_read_b128 v[166:169], v244 offset:41568
	ds_read_b128 v[184:187], v244 offset:46176
	ds_read_b128 v[244:247], v244 offset:50784
	s_setprio 1
	v_mfma_f32_16x16x32_bf16 v[64:67], v[76:79], v[80:83], v[64:67]
	v_mfma_f32_16x16x32_bf16 v[64:67], v[76:79], v[88:91], v[64:67]
	v_mfma_f32_16x16x32_bf16 v[64:67], v[76:79], v[84:87], v[64:67]
	v_mfma_f32_16x16x32_bf16 v[64:67], v[76:79], v[92:95], v[64:67]
	v_add_u32_e32 v249, s40, v212
	s_waitcnt vmcnt(3)
	ds_write_b128 v249, v[142:145]
	s_waitcnt vmcnt(2)
	ds_write_b128 v249, v[138:141] offset:9216
	s_waitcnt lgkmcnt(15)
	v_mfma_f32_32x32x16_bf16 v[48:63], v[96:99], v[80:83], v[48:63]
	s_waitcnt lgkmcnt(15)
	v_mfma_f32_32x32x16_bf16 v[32:47], v[154:157], v[80:83], v[32:47]
	s_waitcnt lgkmcnt(15)
	v_mfma_f32_32x32x16_bf16 v[16:31], v[170:173], v[80:83], v[16:31]
	s_waitcnt lgkmcnt(14)
	v_mfma_f32_32x32x16_bf16 v[0:15], v[232:235], v[80:83], v[0:15]
	s_waitcnt lgkmcnt(13)
	v_mfma_f32_32x32x16_bf16 v[48:63], v[100:103], v[88:91], v[48:63]
	s_waitcnt lgkmcnt(12)
	v_mfma_f32_32x32x16_bf16 v[32:47], v[158:161], v[88:91], v[32:47]
	s_waitcnt lgkmcnt(11)
	v_mfma_f32_32x32x16_bf16 v[16:31], v[174:177], v[88:91], v[16:31]
	s_waitcnt lgkmcnt(10)
	v_mfma_f32_32x32x16_bf16 v[0:15], v[236:239], v[88:91], v[0:15]
	s_waitcnt lgkmcnt(9)
	v_mfma_f32_32x32x16_bf16 v[48:63], v[104:107], v[84:87], v[48:63]
	s_waitcnt lgkmcnt(8)
	v_mfma_f32_32x32x16_bf16 v[32:47], v[162:165], v[84:87], v[32:47]
	s_waitcnt lgkmcnt(7)
	v_mfma_f32_32x32x16_bf16 v[16:31], v[178:181], v[84:87], v[16:31]
	s_waitcnt lgkmcnt(6)
	v_mfma_f32_32x32x16_bf16 v[0:15], v[240:243], v[84:87], v[0:15]
	s_waitcnt lgkmcnt(5)
	v_mfma_f32_32x32x16_bf16 v[48:63], v[108:111], v[92:95], v[48:63]
	s_waitcnt lgkmcnt(4)
	v_mfma_f32_32x32x16_bf16 v[32:47], v[166:169], v[92:95], v[32:47]
	s_waitcnt lgkmcnt(3)
	v_mfma_f32_32x32x16_bf16 v[16:31], v[184:187], v[92:95], v[16:31]
	s_waitcnt lgkmcnt(2)
	v_mfma_f32_32x32x16_bf16 v[0:15], v[244:247], v[92:95], v[0:15]
	s_setprio 0
	s_branch .Lmy_wj4

; __device__ __forceinline__ void at_qk_half(const bool ONLINE, const bool act, const LAS unsigned char* kp, u32x4& pfa, u32x4& pfb, const char* pga, const char* pgb, const bf16x8 (&qf)[4], int q, int q0, int kbase, int hh, float& mrun, f32x16 (&O)[4], f32x16& L, bf16x8 (&pf)[4]) {
;     __builtin_amdgcn_s_setprio(3);
;     bf16x8 kf[8];
; #pragma unroll
;     for (int s = 0; s < 4; ++s) { kf[2 * s] = *(const LAS bf16x8*)(kp + 32 * s); kf[2 * s + 1] = *(const LAS bf16x8*)(kp + 32 * AT_ROWB + 32 * s); }
;     __builtin_amdgcn_sched_barrier(0);
;     pfa = *(const u32x4*)pga; pfb = *(const u32x4*)pgb;
;     __builtin_amdgcn_sched_barrier(0);
;     if (!act) { __builtin_amdgcn_s_setprio(0); return; }
;     f32x16 s0, s1;
; #pragma unroll
;     for (int i = 0; i < 16; ++i) { s0[i] = 0.f; s1[i] = 0.f; }
; #pragma unroll
;     for (int s = 0; s < 4; ++s) { s0 = MFMA32(kf[2 * s], qf[s], s0); s1 = MFMA32(kf[2 * s + 1], qf[s], s1); }
;     __builtin_amdgcn_s_setprio(0);
;     if (kbase + 63 > q0) {
;         const int kb = kbase + 4 * hh;
; #pragma unroll
;         for (int i = 0; i < 16; ++i) { const int kv = kb + (i & 3) + 8 * (i >> 2); if (kv > q) s0[i] = -INFINITY; if (kv + 32 > q) s1[i] = -INFINITY; }
;     }
;     if (ONLINE) {
; #pragma unroll
;         for (int i = 0; i < 16; ++i) { s0[i] -= mrun; s1[i] -= mrun; }
;         float mx = fmaxf(s0[0], s1[0]);
; #pragma unroll
;         for (int i = 1; i < 16; ++i) mx = at_max3(mx, s0[i], s1[i]);
;         mx = half_swap_max(mx);
;         if (__builtin_amdgcn_ballot_w64(mx > 8.f) != 0ull) {
;             const float d = fmaxf(mx, 0.f); const float alpha = __builtin_amdgcn_exp2f(-d); mrun += d;
; #pragma unroll
;             for (int e = 0; e < 4; ++e)
; #pragma unroll
;                 for (int i = 0; i < 16; ++i) O[e][i] *= alpha;
; __device__ __forceinline__ void attn_item(LAS unsigned char* lds, const bf16_t* Q, const bf16_t* Kb, const bf16_t* VT, bf16_t* aout, const float* subg, float lam, float omli, float kbound, int head, int qb) {
;     ...
;             __syncthreads();
;             __builtin_amdgcn_s_setprio(3);
;             { const int jc_ = (j + 2) < ntm1 ? (j + 2) : ntm1; const size_t ko_ = (size_t)jc_ * 8192; const char* pga = bK1 + ko_ + koff; const char* pgb = bK2 + ko_ + koff;
;               at_qk_half(online, kbase <= qmax, stg + kfo, ks0, ks1, pga, pgb, qf, q, q0, kbase, hh, mrun, O, L, pf); }
.Lmy_wj4:
	v_add_u32_e32 v232, s40, v212
	s_bitcmp1_b32 s39, 0
	s_cselect_b32 s42, 0x4800, 0
	s_sub_i32 s43, s1, 63
	s_add_i32 s39, s39, 2
	s_min_i32 s58, s39, s22
	s_lshl_b64 s[40:41], s[58:59], 13
	v_lshl_add_u64 v[100:101], v[204:205], 0, s[40:41]
	v_lshl_add_u64 v[102:103], v[206:207], 0, s[40:41]
	v_add_u32_e32 v104, s42, v230
	s_cmp_gt_i32 s43, s21
	s_waitcnt lgkmcnt(0)
	s_barrier
	s_setprio 3
	ds_read_b128 v[96:99], v104
	ds_read_b128 v[166:169], v104 offset:32
	ds_read_b128 v[162:165], v104 offset:64
	ds_read_b128 v[154:157], v104 offset:96
	ds_read_b128 v[178:181], v104 offset:4608
	ds_read_b128 v[170:173], v104 offset:4640
	ds_read_b128 v[174:177], v104 offset:4672
	ds_read_b128 v[158:161], v104 offset:4704
	global_load_dwordx4 v[142:145], v[100:101], off
	global_load_dwordx4 v[138:141], v[102:103], off
	s_cbranch_scc1 .LBB0_342
	s_cmp_le_i32 s1, s33
	s_cbranch_scc0 .Lmy_slow3
	s_andn2_b64 vcc, exec, s[8:9]
	s_cbranch_vccz .Lmy_slow3
	s_waitcnt lgkmcnt(7)
	v_mfma_f32_32x32x16_bf16 v[96:111], v[96:99], v[126:129], 0
	s_waitcnt lgkmcnt(6)
	v_mfma_f32_32x32x16_bf16 v[96:111], v[166:169], v[122:125], v[96:111]
	s_waitcnt lgkmcnt(5)
	v_mfma_f32_32x32x16_bf16 v[96:111], v[162:165], v[118:121], v[96:111]
	s_waitcnt lgkmcnt(4)
	v_mfma_f32_32x32x16_bf16 v[96:111], v[154:157], v[114:117], v[96:111]
	s_waitcnt lgkmcnt(3)
	v_mfma_f32_32x32x16_bf16 v[80:95], v[178:181], v[126:129], 0
	s_waitcnt lgkmcnt(2)
	v_mfma_f32_32x32x16_bf16 v[80:95], v[170:173], v[122:125], v[80:95]
	s_nop 8
	v_exp_f32_e32 v96, v96
	v_exp_f32_e32 v97, v97
	v_exp_f32_e32 v98, v98
	v_exp_f32_e32 v99, v99
	s_waitcnt lgkmcnt(1)
	v_mfma_f32_32x32x16_bf16 v[80:95], v[174:177], v[118:121], v[80:95]
	v_exp_f32_e32 v100, v100
	v_exp_f32_e32 v101, v101
	v_exp_f32_e32 v102, v102
	v_exp_f32_e32 v103, v103
	s_waitcnt lgkmcnt(0)
	v_mfma_f32_32x32x16_bf16 v[80:95], v[158:161], v[114:117], v[80:95]
	s_setprio 0
	v_exp_f32_e32 v104, v104
	v_exp_f32_e32 v105, v105
	v_exp_f32_e32 v106, v106
	v_exp_f32_e32 v107, v107
	v_exp_f32_e32 v108, v108
	v_exp_f32_e32 v109, v109
	v_exp_f32_e32 v110, v110
	v_exp_f32_e32 v111, v111
	s_nop 3
	v_exp_f32_e32 v154, v80
	v_exp_f32_e32 v155, v81
	v_exp_f32_e32 v156, v82
	v_exp_f32_e32 v157, v83
	v_exp_f32_e32 v158, v84
	v_exp_f32_e32 v159, v85
	v_exp_f32_e32 v160, v86
	v_exp_f32_e32 v161, v87
	v_exp_f32_e32 v162, v88
	v_exp_f32_e32 v163, v89
	v_exp_f32_e32 v164, v90
	v_exp_f32_e32 v165, v91
	v_exp_f32_e32 v166, v92
	v_exp_f32_e32 v167, v93
	v_exp_f32_e32 v168, v94
	v_exp_f32_e32 v169, v95
	v_cvt_pk_bf16_f32 v80, v96, v97
	v_cvt_pk_bf16_f32 v81, v98, v99
	v_cvt_pk_bf16_f32 v82, v100, v101
	v_cvt_pk_bf16_f32 v83, v102, v103
	v_cvt_pk_bf16_f32 v84, v154, v155
	v_cvt_pk_bf16_f32 v85, v156, v157
	v_cvt_pk_bf16_f32 v86, v158, v159
	v_cvt_pk_bf16_f32 v87, v160, v161
	v_cvt_pk_bf16_f32 v88, v104, v105
	v_cvt_pk_bf16_f32 v89, v106, v107
	v_cvt_pk_bf16_f32 v90, v108, v109
	v_cvt_pk_bf16_f32 v91, v110, v111
	v_cvt_pk_bf16_f32 v92, v162, v163
	v_cvt_pk_bf16_f32 v93, v164, v165
	v_cvt_pk_bf16_f32 v94, v166, v167
	v_cvt_pk_bf16_f32 v95, v168, v169
	s_branch .LBB0_342

; #define LAS __attribute__((address_space(3)))
; #define AT_ISSUE_V(jn) do { const int jc_ = (jn) < ntm1 ? (jn) : ntm1; const size_t vo_ = (size_t)jc_ * 16384; vs0 = *(const u32x4*)(bV0 + vo_ + voff); vs1 = *(const u32x4*)(bV1 + vo_ + voff); } while (0)
; #define AT_WRITE_K(jn) do { LAS unsigned char* n_ = lds + ((jn) & 1) * AT_KST; *(LAS u32x4*)(n_ + dK1) = ks0; *(LAS u32x4*)(n_ + dK2) = ks1; } while (0)
; #define AT_WRITE_V(jn) do { LAS unsigned char* n_ = lds + ((jn) & 1) * AT_KST; *(LAS u32x4*)(n_ + dV0) = vs0; *(LAS u32x4*)(n_ + dV1) = vs1; } while (0)
; __device__ __forceinline__ void attn_item(LAS unsigned char* lds, const bf16_t* Q, const bf16_t* Kb, const bf16_t* VT, bf16_t* aout, const float* subg, float lam, float omli, float kbound, int head, int qb) {
;     ...
;         for (int j = 0; j < nt; ++j) {
;             const LAS unsigned char* stg = lds + (j & 1) * AT_KST; const LAS unsigned char* pst = lds + ((j + 1) & 1) * AT_KST; const int kbase = j * 64;
;             AT_ISSUE_V(j + 1);
;             if (j > 0 && kbase - 64 <= qmax) at_pv_half(pst + vfo, pf, O, L);
;             AT_WRITE_K(j + 1);
;             __syncthreads();
;             __builtin_amdgcn_s_setprio(3);
;             { const int jc_ = (j + 2) < ntm1 ? (j + 2) : ntm1; const size_t ko_ = (size_t)jc_ * 8192; const char* pga = bK1 + ko_ + koff; const char* pgb = bK2 + ko_ + koff;
;               at_qk_half(online, kbase <= qmax, stg + kfo, ks0, ks1, pga, pgb, qf, q, q0, kbase, hh, mrun, O, L, pf); }
;             __builtin_amdgcn_s_setprio(3);
;             AT_WRITE_V(j + 1);
;             __syncthreads();
;             __builtin_amdgcn_s_setprio(0);
;         }
.LBB0_342:
	s_setprio 3
	s_waitcnt vmcnt(3)
	ds_write_b128 v232, v[146:149] offset:36864
	s_waitcnt vmcnt(2)
	ds_write_b128 v232, v[150:153] offset:46080
	s_waitcnt lgkmcnt(0)
	s_add_i32 s1, s1, 64
	s_cmp_eq_u32 s0, s38
	s_cbranch_scc1 .Lmy_exit4
	s_mov_b32 s39, s38
	s_add_i32 s38, s39, 1
	s_bitcmp1_b32 s38, 0
	s_cselect_b32 s42, 0x4800, 0
	s_min_i32 s58, s38, s22
	s_lshl_b64 s[40:41], s[58:59], 14
	v_lshl_add_u64 v[96:97], v[208:209], 0, s[40:41]
	v_lshl_add_u64 v[98:99], v[210:211], 0, s[40:41]
	global_load_dwordx4 v[146:149], v[96:97], off
	global_load_dwordx4 v[150:153], v[98:99], off
	s_add_i32 s40, s42, 0
	s_cmp_eq_u32 s39, 0
	s_cselect_b64 s[42:43], -1, 0
	s_add_i32 s41, s1, 0xffffff81
	s_cmp_gt_i32 s41, s21
	s_cselect_b64 s[44:45], -1, 0
	s_or_b64 s[42:43], s[42:43], s[44:45]
	s_and_b64 vcc, exec, s[42:43]
	v_add_u32_e32 v244, s40, v228
	s_barrier
	s_setprio 0
	s_branch .Lmy_top4

; __device__ __forceinline__ void at_qk_half(const bool ONLINE, const bool act, const LAS unsigned char* kp, u32x4& pfa, u32x4& pfb, const char* pga, const char* pgb, const bf16x8 (&qf)[4], int q, int q0, int kbase, int hh, float& mrun, f32x16 (&O)[4], f32x16& L, bf16x8 (&pf)[4]) {
;     __builtin_amdgcn_s_setprio(3);
;     bf16x8 kf[8];
; #pragma unroll
;     for (int s = 0; s < 4; ++s) { kf[2 * s] = *(const LAS bf16x8*)(kp + 32 * s); kf[2 * s + 1] = *(const LAS bf16x8*)(kp + 32 * AT_ROWB + 32 * s); }
;     __builtin_amdgcn_sched_barrier(0);
;     pfa = *(const u32x4*)pga; pfb = *(const u32x4*)pgb;
;     __builtin_amdgcn_sched_barrier(0);
;     if (!act) { __builtin_amdgcn_s_setprio(0); return; }
;     f32x16 s0, s1;
; #pragma unroll
;     for (int i = 0; i < 16; ++i) { s0[i] = 0.f; s1[i] = 0.f; }
; #pragma unroll
;     for (int s = 0; s < 4; ++s) { s0 = MFMA32(kf[2 * s], qf[s], s0); s1 = MFMA32(kf[2 * s + 1], qf[s], s1); }
;     __builtin_amdgcn_s_setprio(0);
;     if (kbase + 63 > q0) {
;         const int kb = kbase + 4 * hh;
; #pragma unroll
;         for (int i = 0; i < 16; ++i) { const int kv = kb + (i & 3) + 8 * (i >> 2); if (kv > q) s0[i] = -INFINITY; if (kv + 32 > q) s1[i] = -INFINITY; }
;     }
;     if (ONLINE) {
; #pragma unroll
;         for (int i = 0; i < 16; ++i) { s0[i] -= mrun; s1[i] -= mrun; }
;         float mx = fmaxf(s0[0], s1[0]);
; #pragma unroll
;         for (int i = 1; i < 16; ++i) mx = at_max3(mx, s0[i], s1[i]);
;         mx = half_swap_max(mx);
;         if (__builtin_amdgcn_ballot_w64(mx > 8.f) != 0ull) {
;             const float d = fmaxf(mx, 0.f); const float alpha = __builtin_amdgcn_exp2f(-d); mrun += d;
; #pragma unroll
;             for (int e = 0; e < 4; ++e)
; __device__ __forceinline__ void attn_item(LAS unsigned char* lds, const bf16_t* Q, const bf16_t* Kb, const bf16_t* VT, bf16_t* aout, const float* subg, float lam, float omli, float kbound, int head, int qb) {
;     ...
;             const LAS unsigned char* stg = lds + (j & 1) * AT_KST; const int kbase = j * 64; const bool act = kbase <= qmax;
;             __builtin_amdgcn_s_setprio(3);
;             { const int jc_ = (j + 1) < ntm1 ? (j + 1) : ntm1; const size_t vo_ = (size_t)jc_ * 16384; const char* pga = bV0 + vo_ + voff; const char* pgb = bV1 + vo_ + voff;
;               at_qk_half(online, act, stg + kfo, vs0, vs1, pga, pgb, qf, q, q0, kbase, hh, mrun, O, L, pf); }
.Lmy_top6:
	ds_read_b128 v[96:99], v104
	ds_read_b128 v[158:161], v104 offset:32
	ds_read_b128 v[154:157], v104 offset:64
	ds_read_b128 v[146:149], v104 offset:96
	ds_read_b128 v[170:173], v104 offset:4608
	ds_read_b128 v[162:165], v104 offset:4640
	ds_read_b128 v[166:169], v104 offset:4672
	ds_read_b128 v[150:153], v104 offset:4704
	global_load_dwordx4 v[138:141], v[100:101], off
	global_load_dwordx4 v[142:145], v[102:103], off
	s_cbranch_scc1 .LBB0_358
	s_cmp_le_i32 s20, s33
	s_cbranch_scc0 .Lmy_slow4
	s_andn2_b64 vcc, exec, s[8:9]
	s_cbranch_vccz .Lmy_slow4
	s_waitcnt lgkmcnt(7)
	v_mfma_f32_32x32x16_bf16 v[96:111], v[96:99], v[126:129], 0
	s_waitcnt lgkmcnt(6)
	v_mfma_f32_32x32x16_bf16 v[96:111], v[158:161], v[122:125], v[96:111]
	s_waitcnt lgkmcnt(5)
	v_mfma_f32_32x32x16_bf16 v[96:111], v[154:157], v[118:121], v[96:111]
	s_waitcnt lgkmcnt(4)
	v_mfma_f32_32x32x16_bf16 v[96:111], v[146:149], v[114:117], v[96:111]
	s_waitcnt lgkmcnt(3)
	v_mfma_f32_32x32x16_bf16 v[80:95], v[170:173], v[126:129], 0
	s_waitcnt lgkmcnt(2)
	v_mfma_f32_32x32x16_bf16 v[80:95], v[162:165], v[122:125], v[80:95]
	s_nop 8
	v_exp_f32_e32 v96, v96
	v_exp_f32_e32 v97, v97
	v_exp_f32_e32 v98, v98
	v_exp_f32_e32 v99, v99
	s_waitcnt lgkmcnt(1)
	v_mfma_f32_32x32x16_bf16 v[80:95], v[166:169], v[118:121], v[80:95]
	v_exp_f32_e32 v100, v100
	v_exp_f32_e32 v101, v101
	v_exp_f32_e32 v102, v102
	v_exp_f32_e32 v103, v103
	s_waitcnt lgkmcnt(0)
	v_mfma_f32_32x32x16_bf16 v[80:95], v[150:153], v[114:117], v[80:95]
	s_setprio 0
	v_exp_f32_e32 v104, v104
	v_exp_f32_e32 v105, v105
	v_exp_f32_e32 v106, v106
	v_exp_f32_e32 v107, v107
	v_exp_f32_e32 v108, v108
	v_exp_f32_e32 v109, v109
	v_exp_f32_e32 v110, v110
	v_exp_f32_e32 v111, v111
	s_nop 3
	v_exp_f32_e32 v146, v80
	v_exp_f32_e32 v147, v81
	v_exp_f32_e32 v148, v82
	v_exp_f32_e32 v149, v83
	v_exp_f32_e32 v150, v84
	v_exp_f32_e32 v151, v85
	v_exp_f32_e32 v152, v86
	v_exp_f32_e32 v153, v87
	v_exp_f32_e32 v154, v88
	v_exp_f32_e32 v155, v89
	v_exp_f32_e32 v156, v90
	v_exp_f32_e32 v157, v91
	v_exp_f32_e32 v158, v92
	v_exp_f32_e32 v159, v93
	v_exp_f32_e32 v160, v94
	v_exp_f32_e32 v161, v95
	v_cvt_pk_bf16_f32 v80, v96, v97
	v_cvt_pk_bf16_f32 v81, v98, v99
	v_cvt_pk_bf16_f32 v82, v100, v101
	v_cvt_pk_bf16_f32 v83, v102, v103
	v_cvt_pk_bf16_f32 v84, v146, v147
	v_cvt_pk_bf16_f32 v85, v148, v149
	v_cvt_pk_bf16_f32 v86, v150, v151
	v_cvt_pk_bf16_f32 v87, v152, v153
	v_cvt_pk_bf16_f32 v88, v104, v105
	v_cvt_pk_bf16_f32 v89, v106, v107
	v_cvt_pk_bf16_f32 v90, v108, v109
	v_cvt_pk_bf16_f32 v91, v110, v111
	v_cvt_pk_bf16_f32 v92, v154, v155
	v_cvt_pk_bf16_f32 v93, v156, v157
	v_cvt_pk_bf16_f32 v94, v158, v159
	v_cvt_pk_bf16_f32 v95, v160, v161
	s_branch .LBB0_358

; #define LAS __attribute__((address_space(3)))
; #define MFMA32(a, b, c) __builtin_amdgcn_mfma_f32_32x32x16_bf16((a), (b), (c), 0, 0, 0)
; #define AT_ISSUE_K(jn) do { const int jc_ = (jn) < ntm1 ? (jn) : ntm1; const size_t ko_ = (size_t)jc_ * 8192; ks0 = *(const u32x4*)(bK1 + ko_ + koff); ks1 = *(const u32x4*)(bK2 + ko_ + koff); } while (0)
; #define AT_WRITE_K(jn) do { LAS unsigned char* n_ = lds + ((jn) & 1) * AT_KST; *(LAS u32x4*)(n_ + dK1) = ks0; *(LAS u32x4*)(n_ + dK2) = ks1; } while (0)
; #define AT_WRITE_V(jn) do { LAS unsigned char* n_ = lds + ((jn) & 1) * AT_KST; *(LAS u32x4*)(n_ + dV0) = vs0; *(LAS u32x4*)(n_ + dV1) = vs1; } while (0)
; __device__ __forceinline__ void at_pv_half(const LAS unsigned char* vp, const bf16x8 (&pf)[4], f32x16 (&O)[4], f32x16& L) {
;     bf16x8 va[8], vb[8];
; #pragma unroll
;     for (int e = 0; e < 2; ++e)
; #pragma unroll
;         for (int ks = 0; ks < 4; ++ks) va[e * 4 + ks] = *(const LAS bf16x8*)(vp + e * 32 * AT_ROWB + 32 * ks);
; #pragma unroll
;     for (int e = 0; e < 2; ++e)
; #pragma unroll
;         for (int ks = 0; ks < 4; ++ks) vb[e * 4 + ks] = *(const LAS bf16x8*)(vp + (2 + e) * 32 * AT_ROWB + 32 * ks);
;     const short one = (short)0x3F80; const bf16x8 ones = {one, one, one, one, one, one, one, one};
;     __builtin_amdgcn_sched_barrier(0);
;     __builtin_amdgcn_s_setprio(1);
; #pragma unroll
;     for (int ks = 0; ks < 4; ++ks) L = MFMA32(ones, pf[ks], L);
;     __builtin_amdgcn_sched_barrier(0);
; #pragma unroll
;     for (int ks = 0; ks < 4; ++ks) { O[0] = MFMA32(va[ks], pf[ks], O[0]); O[1] = MFMA32(va[4 + ks], pf[ks], O[1]); }
; #pragma unroll
;     for (int ks = 0; ks < 4; ++ks) { O[2] = MFMA32(vb[ks], pf[ks], O[2]); O[3] = MFMA32(vb[4 + ks], pf[ks], O[3]); }
;     __builtin_amdgcn_s_setprio(0);
; __device__ __forceinline__ void attn_item(LAS unsigned char* lds, const bf16_t* Q, const bf16_t* Kb, const bf16_t* VT, bf16_t* aout, const float* subg, float lam, float omli, float kbound, int head, int qb) {
;     ...
;             __builtin_amdgcn_s_setprio(3);
;             AT_WRITE_K(j + 1);
;             __syncthreads();
;             __builtin_amdgcn_s_setprio(0);
;             AT_ISSUE_K(j + 2);
;             if (act) at_pv_half(stg + vfo, pf, O, L);
;             AT_WRITE_V(j + 1);
;             __syncthreads();
.LBB0_358:
	s_setprio 3
	s_bitcmp1_b32 s39, 0
	s_cselect_b32 s41, 0x4800, 0
	s_waitcnt lgkmcnt(7)
	v_add_u32_e32 v96, s41, v213
	s_waitcnt vmcnt(3)
	ds_write_b128 v96, v[130:133]
	s_waitcnt vmcnt(2)
	ds_write_b128 v96, v[134:137] offset:9216
	s_waitcnt lgkmcnt(0)
	s_add_i32 s38, s38, 2
	s_min_i32 s58, s38, s22
	s_lshl_b64 s[42:43], s[58:59], 13
	v_lshl_add_u64 v[98:99], v[204:205], 0, s[42:43]
	v_lshl_add_u64 v[100:101], v[206:207], 0, s[42:43]
	global_load_dwordx4 v[130:133], v[98:99], off
	global_load_dwordx4 v[134:137], v[100:101], off
	s_andn2_b64 vcc, exec, s[0:1]
	v_add_u32_e32 v97, s40, v228
	s_barrier
	s_setprio 0
	s_cbranch_vccnz .LBB0_360
	ds_read_b128 v[98:101], v97 offset:36864
	ds_read_b128 v[150:153], v97 offset:41472
	ds_read_b128 v[166:169], v97 offset:46080
	ds_read_b128 v[230:233], v97 offset:50688
	ds_read_b128 v[102:105], v97 offset:36896
	ds_read_b128 v[154:157], v97 offset:41504
	ds_read_b128 v[170:173], v97 offset:46112
	ds_read_b128 v[234:237], v97 offset:50720
	ds_read_b128 v[106:109], v97 offset:36928
	ds_read_b128 v[158:161], v97 offset:41536
	ds_read_b128 v[176:179], v97 offset:46144
	ds_read_b128 v[238:241], v97 offset:50752
	ds_read_b128 v[146:149], v97 offset:36960
	ds_read_b128 v[162:165], v97 offset:41568
	ds_read_b128 v[184:187], v97 offset:46176
	ds_read_b128 v[242:245], v97 offset:50784
	s_setprio 1
	v_mfma_f32_16x16x32_bf16 v[64:67], v[76:79], v[80:83], v[64:67]
	v_mfma_f32_16x16x32_bf16 v[64:67], v[76:79], v[88:91], v[64:67]
	v_mfma_f32_16x16x32_bf16 v[64:67], v[76:79], v[84:87], v[64:67]
	v_mfma_f32_16x16x32_bf16 v[64:67], v[76:79], v[92:95], v[64:67]
	s_waitcnt vmcnt(3)
	ds_write_b128 v96, v[138:141] offset:36864
	s_waitcnt vmcnt(2)
	ds_write_b128 v96, v[142:145] offset:46080
	s_waitcnt lgkmcnt(15)
	v_mfma_f32_32x32x16_bf16 v[48:63], v[98:101], v[80:83], v[48:63]
	s_waitcnt lgkmcnt(15)
	v_mfma_f32_32x32x16_bf16 v[32:47], v[150:153], v[80:83], v[32:47]
	s_waitcnt lgkmcnt(15)
	v_mfma_f32_32x32x16_bf16 v[16:31], v[166:169], v[80:83], v[16:31]
	s_waitcnt lgkmcnt(14)
	v_mfma_f32_32x32x16_bf16 v[0:15], v[230:233], v[80:83], v[0:15]
	s_waitcnt lgkmcnt(13)
	v_mfma_f32_32x32x16_bf16 v[48:63], v[102:105], v[88:91], v[48:63]
	s_waitcnt lgkmcnt(12)
	v_mfma_f32_32x32x16_bf16 v[32:47], v[154:157], v[88:91], v[32:47]
	s_waitcnt lgkmcnt(11)
	v_mfma_f32_32x32x16_bf16 v[16:31], v[170:173], v[88:91], v[16:31]
	s_waitcnt lgkmcnt(10)
	v_mfma_f32_32x32x16_bf16 v[0:15], v[234:237], v[88:91], v[0:15]
	s_waitcnt lgkmcnt(9)
	v_mfma_f32_32x32x16_bf16 v[48:63], v[106:109], v[84:87], v[48:63]
	s_waitcnt lgkmcnt(8)
	v_mfma_f32_32x32x16_bf16 v[32:47], v[158:161], v[84:87], v[32:47]
	s_waitcnt lgkmcnt(7)
	v_mfma_f32_32x32x16_bf16 v[16:31], v[176:179], v[84:87], v[16:31]
	s_waitcnt lgkmcnt(6)
	v_mfma_f32_32x32x16_bf16 v[0:15], v[238:241], v[84:87], v[0:15]
	s_waitcnt lgkmcnt(5)
	v_mfma_f32_32x32x16_bf16 v[48:63], v[146:149], v[92:95], v[48:63]
	s_waitcnt lgkmcnt(4)
	v_mfma_f32_32x32x16_bf16 v[32:47], v[162:165], v[92:95], v[32:47]
	s_waitcnt lgkmcnt(3)
	v_mfma_f32_32x32x16_bf16 v[16:31], v[184:187], v[92:95], v[16:31]
	s_waitcnt lgkmcnt(2)
	v_mfma_f32_32x32x16_bf16 v[0:15], v[242:245], v[92:95], v[0:15]
	s_setprio 0
	s_branch .Lmy_wj6

; #define LAS __attribute__((address_space(3)))
; #define AT_ISSUE_K(jn) do { const int jc_ = (jn) < ntm1 ? (jn) : ntm1; const size_t ko_ = (size_t)jc_ * 8192; ks0 = *(const u32x4*)(bK1 + ko_ + koff); ks1 = *(const u32x4*)(bK2 + ko_ + koff); } while (0)
; #define AT_WRITE_K(jn) do { LAS unsigned char* n_ = lds + ((jn) & 1) * AT_KST; *(LAS u32x4*)(n_ + dK1) = ks0; *(LAS u32x4*)(n_ + dK2) = ks1; } while (0)
; #define AT_WRITE_V(jn) do { LAS unsigned char* n_ = lds + ((jn) & 1) * AT_KST; *(LAS u32x4*)(n_ + dV0) = vs0; *(LAS u32x4*)(n_ + dV1) = vs1; } while (0)
; __device__ __forceinline__ void attn_item(LAS unsigned char* lds, const bf16_t* Q, const bf16_t* Kb, const bf16_t* VT, bf16_t* aout, const float* subg, float lam, float omli, float kbound, int head, int qb) {
;     ...
;         for (int j = 0; j < nt; ++j) {
;             const LAS unsigned char* stg = lds + (j & 1) * AT_KST; const int kbase = j * 64; const bool act = kbase <= qmax;
;             __builtin_amdgcn_s_setprio(3);
;             { const int jc_ = (j + 1) < ntm1 ? (j + 1) : ntm1; const size_t vo_ = (size_t)jc_ * 16384; const char* pga = bV0 + vo_ + voff; const char* pgb = bV1 + vo_ + voff;
;               at_qk_half(online, act, stg + kfo, vs0, vs1, pga, pgb, qf, q, q0, kbase, hh, mrun, O, L, pf); }
;             __builtin_amdgcn_s_setprio(3);
;             AT_WRITE_K(j + 1);
;             __syncthreads();
;             __builtin_amdgcn_s_setprio(0);
;             AT_ISSUE_K(j + 2);
;             if (act) at_pv_half(stg + vfo, pf, O, L);
;             AT_WRITE_V(j + 1);
;             __syncthreads();
;         }
.Lmy_wj6:
	s_add_i32 s20, s20, 64
	s_cmp_eq_u32 s19, s39
	s_cbranch_scc1 .Lmy_exit6
	s_mov_b32 s38, s39
	s_bitcmp1_b32 s38, 0
	s_cselect_b32 s0, 0x4800, 0
	s_add_i32 s40, s0, 0
	s_sub_i32 s41, s20, 63
	s_cmp_le_i32 s41, s21
	s_cselect_b64 s[0:1], -1, 0
	s_add_i32 s39, s38, 1
	s_min_i32 s58, s39, s22
	s_lshl_b64 s[42:43], s[58:59], 14
	s_cmp_gt_i32 s41, s21
	v_lshl_add_u64 v[100:101], v[208:209], 0, s[42:43]
	v_lshl_add_u64 v[102:103], v[210:211], 0, s[42:43]
	v_add_u32_e32 v104, s40, v229
	s_waitcnt lgkmcnt(0)
	s_barrier
	s_setprio 3
	s_branch .Lmy_top6
